# grid barrier: waiting workgroups watch the cross-XCC release word directly, skipping the per-XCC relay hop
# baseline (speedup 1.0000x reference)
.LBB0_881:
	v_readlane_b32 s10, v253, 54
	v_readlane_b32 s11, v253, 55
	s_add_i32 s18, s18, 1
	s_mov_b64 s[12:13], -1
	s_nop 2
	global_load_dword v0, v193, s[10:11] sc1
	s_waitcnt vmcnt(0)
	v_cmp_ne_u32_e32 vcc, v0, v1
	s_orn2_b64 s[10:11], vcc, exec
	s_branch .LBB0_878
